# all three GEMM K-loops: LDS-DMA loads use SGPR base + 32-bit lane offset (saddr form), the 16 per-iteration 64-bit VALU address adds removed
# baseline (speedup 1.0000x reference)
; #define PG8_STAGE(bufoff, gbase, voff) do { _Pragma("unroll") for (int _i = 0; _i < 2; ++_i) \
;         __builtin_amdgcn_global_load_lds((const unsigned*)((const char*)(gbase) + (voff)[_i]), (LAS unsigned*)(lds + (bufoff) + ldsw + _i * 8192), 16, 0, 0); } while (0)
; #define PG8_LDA(dst, b, h) do { _Pragma("unroll") for (int m = 0; m < 4; ++m) _Pragma("unroll") for (int k = 0; k < 2; ++k) dst[m][k] = *(const LAS bf16x8*)(lds + PG8_SA(b, h) + aoff + m * 2048 + k * 1024); } while (0)
; #define PG8_LDB(dst, b, h) do { _Pragma("unroll") for (int n = 0; n < 2; ++n) _Pragma("unroll") for (int k = 0; k < 2; ++k) dst[n][k] = *(const LAS bf16x8*)(lds + PG8_SB(b, h) + boff + n * 2048 + k * 1024); } while (0)
; #define PG8_MMA(ai, bj, At, Bt) do { __builtin_amdgcn_s_setprio(1); _Pragma("unroll") for (int m = 0; m < 4; ++m) _Pragma("unroll") for (int n = 0; n < 2; ++n) _Pragma("unroll") for (int k = 0; k < 2; ++k) \
;         acc[ai][bj][m][n] = __builtin_amdgcn_mfma_f32_16x16x32_bf16(Bt[n][k], At[m][k], acc[ai][bj][m][n], 0, 0, 0); __builtin_amdgcn_s_setprio(0); } while (0)
; #define PG8_WAIT_V(n) asm volatile("s_waitcnt vmcnt(" #n ")" ::: "memory")
; #define PG8_WAIT_L(n) asm volatile("s_waitcnt lgkmcnt(" #n ")" ::: "memory")
; #define PG8_BAR __builtin_amdgcn_s_barrier()
; #define PG8_SCHED __builtin_amdgcn_sched_barrier(0)
; template <class Epi, class Sched>
; __device__ __forceinline__ void gemm_phase(LAS unsigned char* lds, const Gemm g, const Sched& S, const Epi& E) {
;     ...
;             PG8_LDB(B0, 0, 0); PG8_LDB(B1, 0, 1); PG8_SCHED; PG8_LDA(At, 0, 0); PG8_STAGE(PG8_SA(1, 1), a1 + hstep, voffA);
;             PG8_WAIT_V(8); PG8_WAIT_L(0); PG8_BAR; PG8_MMA(0, 0, At, B0); PG8_MMA(0, 1, At, B1); PG8_BAR; PG8_SCHED;
;             PG8_LDA(At, 0, 1); PG8_STAGE(PG8_SB(0, 0), b2, voffB); PG8_STAGE(PG8_SB(0, 1), b2 + hstep, voffB); PG8_STAGE(PG8_SA(0, 0), a2, voffA);
;             PG8_WAIT_V(8); PG8_WAIT_L(0); PG8_BAR; PG8_MMA(1, 0, At, B0); PG8_MMA(1, 1, At, B1); PG8_BAR; PG8_SCHED;
.LBB0_503:
	s_add_u32 s16, s14, 0xfffc0080
	s_addc_u32 s17, s15, -1
	s_add_i32 s41, 0, 0x10000
	s_cmp_eq_u32 s40, 12
	s_cselect_b32 s19, s7, s17
	s_cselect_b32 s18, s8, s16
	s_cselect_b32 s17, s12, s33
	s_cselect_b32 s16, s13, s21
	s_add_i32 s51, 0, 0x14000
	v_add_u32_e32 v84, s41, v168
	v_add_u32_e32 v170, s51, v168
	ds_read_b128 v[72:75], v84
	ds_read_b128 v[76:79], v84 offset:1024
	ds_read_b128 v[80:83], v84 offset:2048
	ds_read_b128 v[84:87], v84 offset:3072
	ds_read_b128 v[154:157], v170
	ds_read_b128 v[158:161], v170 offset:1024
	ds_read_b128 v[162:165], v170 offset:2048
	ds_read_b128 v[170:173], v170 offset:3072
	s_add_i32 m0, s26, 0xc000
	ds_read_b128 v[174:177], v169
	ds_read_b128 v[192:195], v169 offset:1024
	ds_read_b128 v[196:199], v169 offset:2048
	ds_read_b128 v[200:203], v169 offset:3072
	ds_read_b128 v[204:207], v169 offset:4096
	ds_read_b128 v[208:211], v169 offset:5120
	ds_read_b128 v[212:215], v169 offset:6144
	ds_read_b128 v[230:233], v169 offset:7168
	global_load_lds_dwordx4 v150, s[14:15]
	s_add_i32 m0, s26, 0xe000
	s_nop 0
	global_load_lds_dwordx4 v152, s[14:15]
	s_waitcnt vmcnt(8)
	s_waitcnt lgkmcnt(0)
	s_barrier
	s_setprio 1
	s_waitcnt lgkmcnt(0)
	v_mfma_f32_16x16x32_bf16 v[140:143], v[72:75], v[174:177], v[140:143]
	v_mfma_f32_16x16x32_bf16 v[136:139], v[80:83], v[174:177], v[136:139]
	v_mfma_f32_16x16x32_bf16 v[124:127], v[72:75], v[196:199], v[124:127]
	v_mfma_f32_16x16x32_bf16 v[120:123], v[80:83], v[196:199], v[120:123]
	v_mfma_f32_16x16x32_bf16 v[108:111], v[72:75], v[204:207], v[108:111]
	v_mfma_f32_16x16x32_bf16 v[104:107], v[80:83], v[204:207], v[104:107]
	v_mfma_f32_16x16x32_bf16 v[92:95], v[72:75], v[212:215], v[92:95]
	v_mfma_f32_16x16x32_bf16 v[88:91], v[80:83], v[212:215], v[88:91]
	v_mfma_f32_16x16x32_bf16 v[140:143], v[76:79], v[192:195], v[140:143]
	v_mfma_f32_16x16x32_bf16 v[136:139], v[84:87], v[192:195], v[136:139]
	v_mfma_f32_16x16x32_bf16 v[124:127], v[76:79], v[200:203], v[124:127]
	v_mfma_f32_16x16x32_bf16 v[120:123], v[84:87], v[200:203], v[120:123]
	v_mfma_f32_16x16x32_bf16 v[108:111], v[76:79], v[208:211], v[108:111]
	v_mfma_f32_16x16x32_bf16 v[104:107], v[84:87], v[208:211], v[104:107]
	v_mfma_f32_16x16x32_bf16 v[92:95], v[76:79], v[230:233], v[92:95]
	v_mfma_f32_16x16x32_bf16 v[88:91], v[84:87], v[230:233], v[88:91]
	s_setprio 0
	s_setprio 1
	v_mfma_f32_16x16x32_bf16 v[132:135], v[154:157], v[174:177], v[132:135]
	v_mfma_f32_16x16x32_bf16 v[128:131], v[162:165], v[174:177], v[128:131]
	v_mfma_f32_16x16x32_bf16 v[116:119], v[154:157], v[196:199], v[116:119]
	v_mfma_f32_16x16x32_bf16 v[112:115], v[162:165], v[196:199], v[112:115]
	v_mfma_f32_16x16x32_bf16 v[100:103], v[154:157], v[204:207], v[100:103]
	v_mfma_f32_16x16x32_bf16 v[96:99], v[162:165], v[204:207], v[96:99]
	v_mfma_f32_16x16x32_bf16 v[68:71], v[154:157], v[212:215], v[68:71]
	v_mfma_f32_16x16x32_bf16 v[64:67], v[162:165], v[212:215], v[64:67]
	v_mfma_f32_16x16x32_bf16 v[132:135], v[158:161], v[192:195], v[132:135]
	v_mfma_f32_16x16x32_bf16 v[128:131], v[170:173], v[192:195], v[128:131]
	v_mfma_f32_16x16x32_bf16 v[116:119], v[158:161], v[200:203], v[116:119]
	v_mfma_f32_16x16x32_bf16 v[112:115], v[170:173], v[200:203], v[112:115]
	v_mfma_f32_16x16x32_bf16 v[100:103], v[158:161], v[208:211], v[100:103]
	v_mfma_f32_16x16x32_bf16 v[96:99], v[170:173], v[208:211], v[96:99]
	v_mfma_f32_16x16x32_bf16 v[68:71], v[158:161], v[230:233], v[68:71]
	v_mfma_f32_16x16x32_bf16 v[64:67], v[170:173], v[230:233], v[64:67]
	s_setprio 0
	s_barrier
	s_add_i32 s41, s41, s23
	s_mov_b32 m0, s41
	ds_read_b128 v[174:177], v169 offset:16384
	ds_read_b128 v[192:195], v169 offset:17408
	ds_read_b128 v[196:199], v169 offset:18432
	ds_read_b128 v[200:203], v169 offset:19456
	ds_read_b128 v[204:207], v169 offset:20480
	ds_read_b128 v[208:211], v169 offset:21504
	ds_read_b128 v[212:215], v169 offset:22528
	ds_read_b128 v[230:233], v169 offset:23552
	global_load_lds_dwordx4 v184, s[16:17]
	s_add_i32 m0, s41, 0x2000
	s_add_u32 s42, s16, 0x40000
	s_addc_u32 s43, s17, 0
	s_add_i32 s41, s51, s23
	global_load_lds_dwordx4 v148, s[16:17]
	s_mov_b32 m0, s41
	s_nop 0
	global_load_lds_dwordx4 v184, s[42:43]
	s_add_i32 m0, s41, 0x2000
	s_nop 0
	global_load_lds_dwordx4 v148, s[42:43]
	s_mov_b32 m0, s26
	s_nop 0
	global_load_lds_dwordx4 v144, s[18:19]
	s_mov_b32 m0, s27
	s_nop 0
	global_load_lds_dwordx4 v146, s[18:19]
	s_waitcnt vmcnt(8)
	s_waitcnt lgkmcnt(0)
	s_barrier
	s_setprio 1
	s_waitcnt lgkmcnt(0)
	v_mfma_f32_16x16x32_bf16 v[60:63], v[72:75], v[174:177], v[60:63]
	v_mfma_f32_16x16x32_bf16 v[56:59], v[80:83], v[174:177], v[56:59]
	v_mfma_f32_16x16x32_bf16 v[44:47], v[72:75], v[196:199], v[44:47]
	v_mfma_f32_16x16x32_bf16 v[40:43], v[80:83], v[196:199], v[40:43]
	v_mfma_f32_16x16x32_bf16 v[28:31], v[72:75], v[204:207], v[28:31]
	v_mfma_f32_16x16x32_bf16 v[24:27], v[80:83], v[204:207], v[24:27]
	v_mfma_f32_16x16x32_bf16 v[12:15], v[72:75], v[212:215], v[12:15]
	v_mfma_f32_16x16x32_bf16 v[8:11], v[80:83], v[212:215], v[8:11]
	v_mfma_f32_16x16x32_bf16 v[60:63], v[76:79], v[192:195], v[60:63]
	v_mfma_f32_16x16x32_bf16 v[56:59], v[84:87], v[192:195], v[56:59]
	v_mfma_f32_16x16x32_bf16 v[44:47], v[76:79], v[200:203], v[44:47]
	v_mfma_f32_16x16x32_bf16 v[40:43], v[84:87], v[200:203], v[40:43]
	v_mfma_f32_16x16x32_bf16 v[28:31], v[76:79], v[208:211], v[28:31]
	v_mfma_f32_16x16x32_bf16 v[24:27], v[84:87], v[208:211], v[24:27]
	v_mfma_f32_16x16x32_bf16 v[12:15], v[76:79], v[230:233], v[12:15]
	v_mfma_f32_16x16x32_bf16 v[8:11], v[84:87], v[230:233], v[8:11]
	s_setprio 0
	s_setprio 1
	v_mfma_f32_16x16x32_bf16 v[52:55], v[154:157], v[174:177], v[52:55]
	v_mfma_f32_16x16x32_bf16 v[48:51], v[162:165], v[174:177], v[48:51]
	v_mfma_f32_16x16x32_bf16 v[36:39], v[154:157], v[196:199], v[36:39]
	v_mfma_f32_16x16x32_bf16 v[32:35], v[162:165], v[196:199], v[32:35]
	v_mfma_f32_16x16x32_bf16 v[20:23], v[154:157], v[204:207], v[20:23]
	v_mfma_f32_16x16x32_bf16 v[16:19], v[162:165], v[204:207], v[16:19]
	v_mfma_f32_16x16x32_bf16 v[4:7], v[154:157], v[212:215], v[4:7]
	v_mfma_f32_16x16x32_bf16 v[0:3], v[162:165], v[212:215], v[0:3]
	v_mfma_f32_16x16x32_bf16 v[52:55], v[158:161], v[192:195], v[52:55]
	v_mfma_f32_16x16x32_bf16 v[48:51], v[170:173], v[192:195], v[48:51]
	v_mfma_f32_16x16x32_bf16 v[36:39], v[158:161], v[200:203], v[36:39]
	v_mfma_f32_16x16x32_bf16 v[32:35], v[170:173], v[200:203], v[32:35]
	v_mfma_f32_16x16x32_bf16 v[20:23], v[158:161], v[208:211], v[20:23]
	v_mfma_f32_16x16x32_bf16 v[16:19], v[170:173], v[208:211], v[16:19]
	v_mfma_f32_16x16x32_bf16 v[4:7], v[158:161], v[230:233], v[4:7]
	v_mfma_f32_16x16x32_bf16 v[0:3], v[170:173], v[230:233], v[0:3]
	s_setprio 0
	s_barrier
; #define PG8_STAGE(bufoff, gbase, voff) do { _Pragma("unroll") for (int _i = 0; _i < 2; ++_i) \
;         __builtin_amdgcn_global_load_lds((const unsigned*)((const char*)(gbase) + (voff)[_i]), (LAS unsigned*)(lds + (bufoff) + ldsw + _i * 8192), 16, 0, 0); } while (0)
; #define PG8_LDA(dst, b, h) do { _Pragma("unroll") for (int m = 0; m < 4; ++m) _Pragma("unroll") for (int k = 0; k < 2; ++k) dst[m][k] = *(const LAS bf16x8*)(lds + PG8_SA(b, h) + aoff + m * 2048 + k * 1024); } while (0)
; #define PG8_LDB(dst, b, h) do { _Pragma("unroll") for (int n = 0; n < 2; ++n) _Pragma("unroll") for (int k = 0; k < 2; ++k) dst[n][k] = *(const LAS bf16x8*)(lds + PG8_SB(b, h) + boff + n * 2048 + k * 1024); } while (0)
; #define PG8_MMA(ai, bj, At, Bt) do { __builtin_amdgcn_s_setprio(1); _Pragma("unroll") for (int m = 0; m < 4; ++m) _Pragma("unroll") for (int n = 0; n < 2; ++n) _Pragma("unroll") for (int k = 0; k < 2; ++k) \
;         acc[ai][bj][m][n] = __builtin_amdgcn_mfma_f32_16x16x32_bf16(Bt[n][k], At[m][k], acc[ai][bj][m][n], 0, 0, 0); __builtin_amdgcn_s_setprio(0); } while (0)
; #define PG8_WAIT_V(n) asm volatile("s_waitcnt vmcnt(" #n ")" ::: "memory")
; #define PG8_WAIT_L(n) asm volatile("s_waitcnt lgkmcnt(" #n ")" ::: "memory")
; #define PG8_BAR __builtin_amdgcn_s_barrier()
; #define PG8_SCHED __builtin_amdgcn_sched_barrier(0)
; template <class Epi, class Sched>
; __device__ __forceinline__ void gemm_phase(LAS unsigned char* lds, const Gemm g, const Sched& S, const Epi& E) {
;     ...
;         for (int t = 0; t < nt; t += 2) {
;     ...
;             PG8_LDB(B0, 1, 0); PG8_LDB(B1, 1, 1); PG8_SCHED; PG8_LDA(At, 1, 0); PG8_STAGE(PG8_SA(0, 1), a2 + hstep, voffA);
;             PG8_WAIT_V(8); PG8_WAIT_L(0); PG8_BAR; PG8_MMA(0, 0, At, B0); PG8_MMA(0, 1, At, B1); PG8_BAR; PG8_SCHED;
;             PG8_LDA(At, 1, 1); PG8_STAGE(PG8_SB(1, 0), b3, voffB); PG8_STAGE(PG8_SB(1, 1), b3 + hstep, voffB); PG8_STAGE(PG8_SA(1, 0), a3, voffA);
;             PG8_WAIT_V(8); PG8_WAIT_L(0); PG8_BAR; PG8_MMA(1, 0, At, B0); PG8_MMA(1, 1, At, B1); PG8_BAR; PG8_SCHED;
;         }
	s_add_i32 s41, 0, 0x18000
	s_add_i32 s42, 0, 0x1c000
	v_add_u32_e32 v84, s41, v168
	v_add_u32_e32 v170, s42, v168
	ds_read_b128 v[72:75], v84
	ds_read_b128 v[76:79], v84 offset:1024
	ds_read_b128 v[80:83], v84 offset:2048
	ds_read_b128 v[84:87], v84 offset:3072
	ds_read_b128 v[154:157], v170
	ds_read_b128 v[158:161], v170 offset:1024
	ds_read_b128 v[162:165], v170 offset:2048
	ds_read_b128 v[170:173], v170 offset:3072
	s_add_u32 s18, s18, 0x40000
	s_addc_u32 s19, s19, 0
	s_mov_b32 m0, s28
	ds_read_b128 v[174:177], v169 offset:32768
	ds_read_b128 v[192:195], v169 offset:33792
	ds_read_b128 v[196:199], v169 offset:34816
	ds_read_b128 v[200:203], v169 offset:35840
	ds_read_b128 v[204:207], v169 offset:36864
	ds_read_b128 v[208:211], v169 offset:37888
	ds_read_b128 v[212:215], v169 offset:38912
	ds_read_b128 v[230:233], v169 offset:39936
	global_load_lds_dwordx4 v144, s[18:19]
	s_mov_b32 m0, s29
	s_nop 0
	global_load_lds_dwordx4 v146, s[18:19]
	s_waitcnt vmcnt(8)
	s_waitcnt lgkmcnt(0)
	s_barrier
	s_setprio 1
	s_waitcnt lgkmcnt(0)
	v_mfma_f32_16x16x32_bf16 v[140:143], v[72:75], v[174:177], v[140:143]
	v_mfma_f32_16x16x32_bf16 v[136:139], v[80:83], v[174:177], v[136:139]
	v_mfma_f32_16x16x32_bf16 v[124:127], v[72:75], v[196:199], v[124:127]
	v_mfma_f32_16x16x32_bf16 v[120:123], v[80:83], v[196:199], v[120:123]
	v_mfma_f32_16x16x32_bf16 v[108:111], v[72:75], v[204:207], v[108:111]
	v_mfma_f32_16x16x32_bf16 v[104:107], v[80:83], v[204:207], v[104:107]
	v_mfma_f32_16x16x32_bf16 v[92:95], v[72:75], v[212:215], v[92:95]
	v_mfma_f32_16x16x32_bf16 v[88:91], v[80:83], v[212:215], v[88:91]
	v_mfma_f32_16x16x32_bf16 v[140:143], v[76:79], v[192:195], v[140:143]
	v_mfma_f32_16x16x32_bf16 v[136:139], v[84:87], v[192:195], v[136:139]
	v_mfma_f32_16x16x32_bf16 v[124:127], v[76:79], v[200:203], v[124:127]
	v_mfma_f32_16x16x32_bf16 v[120:123], v[84:87], v[200:203], v[120:123]
	v_mfma_f32_16x16x32_bf16 v[108:111], v[76:79], v[208:211], v[108:111]
	v_mfma_f32_16x16x32_bf16 v[104:107], v[84:87], v[208:211], v[104:107]
	v_mfma_f32_16x16x32_bf16 v[92:95], v[76:79], v[230:233], v[92:95]
	v_mfma_f32_16x16x32_bf16 v[88:91], v[84:87], v[230:233], v[88:91]
	s_setprio 0
	s_setprio 1
	v_mfma_f32_16x16x32_bf16 v[132:135], v[154:157], v[174:177], v[132:135]
	v_mfma_f32_16x16x32_bf16 v[128:131], v[162:165], v[174:177], v[128:131]
	v_mfma_f32_16x16x32_bf16 v[116:119], v[154:157], v[196:199], v[116:119]
	v_mfma_f32_16x16x32_bf16 v[112:115], v[162:165], v[196:199], v[112:115]
	v_mfma_f32_16x16x32_bf16 v[100:103], v[154:157], v[204:207], v[100:103]
	v_mfma_f32_16x16x32_bf16 v[96:99], v[162:165], v[204:207], v[96:99]
	v_mfma_f32_16x16x32_bf16 v[68:71], v[154:157], v[212:215], v[68:71]
	v_mfma_f32_16x16x32_bf16 v[64:67], v[162:165], v[212:215], v[64:67]
	v_mfma_f32_16x16x32_bf16 v[132:135], v[158:161], v[192:195], v[132:135]
	v_mfma_f32_16x16x32_bf16 v[128:131], v[170:173], v[192:195], v[128:131]
	v_mfma_f32_16x16x32_bf16 v[116:119], v[158:161], v[200:203], v[116:119]
	v_mfma_f32_16x16x32_bf16 v[112:115], v[170:173], v[200:203], v[112:115]
	v_mfma_f32_16x16x32_bf16 v[100:103], v[158:161], v[208:211], v[100:103]
	v_mfma_f32_16x16x32_bf16 v[96:99], v[170:173], v[208:211], v[96:99]
	v_mfma_f32_16x16x32_bf16 v[68:71], v[158:161], v[230:233], v[68:71]
	v_mfma_f32_16x16x32_bf16 v[64:67], v[170:173], v[230:233], v[64:67]
	s_setprio 0
	s_barrier
	s_add_u32 s16, s16, 0x80
	s_addc_u32 s17, s17, 0
	s_add_i32 m0, s41, s23
	ds_read_b128 v[174:177], v169 offset:49152
	ds_read_b128 v[192:195], v169 offset:50176
	ds_read_b128 v[196:199], v169 offset:51200
	ds_read_b128 v[200:203], v169 offset:52224
	ds_read_b128 v[204:207], v169 offset:53248
	ds_read_b128 v[208:211], v169 offset:54272
	ds_read_b128 v[212:215], v169 offset:55296
	ds_read_b128 v[230:233], v169 offset:56320
	global_load_lds_dwordx4 v184, s[16:17]
	s_add_i32 m0, m0, 0x2000
	s_nop 0
	global_load_lds_dwordx4 v148, s[16:17]
	s_add_u32 s16, s16, 0x40000
	s_addc_u32 s17, s17, 0
	s_add_i32 m0, s42, s23
	s_nop 0
	global_load_lds_dwordx4 v184, s[16:17]
	s_add_i32 m0, m0, 0x2000
	s_nop 0
	global_load_lds_dwordx4 v148, s[16:17]
	s_add_u32 s18, s18, 0xfffc0080
	s_addc_u32 s19, s19, -1
	s_mov_b32 m0, s34
	s_nop 0
	global_load_lds_dwordx4 v144, s[18:19]
	s_mov_b32 m0, s35
	s_nop 0
	global_load_lds_dwordx4 v146, s[18:19]
	s_waitcnt vmcnt(8)
	s_waitcnt lgkmcnt(0)
	s_barrier
	s_setprio 1
	s_waitcnt lgkmcnt(0)
	v_mfma_f32_16x16x32_bf16 v[60:63], v[72:75], v[174:177], v[60:63]
	v_mfma_f32_16x16x32_bf16 v[56:59], v[80:83], v[174:177], v[56:59]
	v_mfma_f32_16x16x32_bf16 v[44:47], v[72:75], v[196:199], v[44:47]
	v_mfma_f32_16x16x32_bf16 v[40:43], v[80:83], v[196:199], v[40:43]
	v_mfma_f32_16x16x32_bf16 v[28:31], v[72:75], v[204:207], v[28:31]
	v_mfma_f32_16x16x32_bf16 v[24:27], v[80:83], v[204:207], v[24:27]
	v_mfma_f32_16x16x32_bf16 v[12:15], v[72:75], v[212:215], v[12:15]
	v_mfma_f32_16x16x32_bf16 v[8:11], v[80:83], v[212:215], v[8:11]
	v_mfma_f32_16x16x32_bf16 v[60:63], v[76:79], v[192:195], v[60:63]
	v_mfma_f32_16x16x32_bf16 v[56:59], v[84:87], v[192:195], v[56:59]
	v_mfma_f32_16x16x32_bf16 v[44:47], v[76:79], v[200:203], v[44:47]
	v_mfma_f32_16x16x32_bf16 v[40:43], v[84:87], v[200:203], v[40:43]
	v_mfma_f32_16x16x32_bf16 v[28:31], v[76:79], v[208:211], v[28:31]
	v_mfma_f32_16x16x32_bf16 v[24:27], v[84:87], v[208:211], v[24:27]
	v_mfma_f32_16x16x32_bf16 v[12:15], v[76:79], v[230:233], v[12:15]
	v_mfma_f32_16x16x32_bf16 v[8:11], v[84:87], v[230:233], v[8:11]
	s_setprio 0
	s_setprio 1
	v_mfma_f32_16x16x32_bf16 v[52:55], v[154:157], v[174:177], v[52:55]
	v_mfma_f32_16x16x32_bf16 v[48:51], v[162:165], v[174:177], v[48:51]
	v_mfma_f32_16x16x32_bf16 v[36:39], v[154:157], v[196:199], v[36:39]
	v_mfma_f32_16x16x32_bf16 v[32:35], v[162:165], v[196:199], v[32:35]
	v_mfma_f32_16x16x32_bf16 v[20:23], v[154:157], v[204:207], v[20:23]
	v_mfma_f32_16x16x32_bf16 v[16:19], v[162:165], v[204:207], v[16:19]
	v_mfma_f32_16x16x32_bf16 v[4:7], v[154:157], v[212:215], v[4:7]
	v_mfma_f32_16x16x32_bf16 v[0:3], v[162:165], v[212:215], v[0:3]
	v_mfma_f32_16x16x32_bf16 v[52:55], v[158:161], v[192:195], v[52:55]
	v_mfma_f32_16x16x32_bf16 v[48:51], v[170:173], v[192:195], v[48:51]
	v_mfma_f32_16x16x32_bf16 v[36:39], v[158:161], v[200:203], v[36:39]
	v_mfma_f32_16x16x32_bf16 v[32:35], v[170:173], v[200:203], v[32:35]
	v_mfma_f32_16x16x32_bf16 v[20:23], v[158:161], v[208:211], v[20:23]
	v_mfma_f32_16x16x32_bf16 v[16:19], v[170:173], v[208:211], v[16:19]
	v_mfma_f32_16x16x32_bf16 v[4:7], v[158:161], v[230:233], v[4:7]
	v_mfma_f32_16x16x32_bf16 v[0:3], v[170:173], v[230:233], v[0:3]
	s_setprio 0
	s_barrier
	s_add_i32 s40, s40, 2
	s_add_u32 s14, s14, 0x100
	s_addc_u32 s15, s15, 0
	s_add_u32 s21, s21, 0x100
	s_addc_u32 s33, s33, 0
	s_cmp_gt_u32 s40, 13
	s_cbranch_scc0 .LBB0_503
	s_and_b64 vcc, exec, s[48:49]
	s_cbranch_vccz .LBB0_506
	s_barrier

; #define PG8_STAGE(bufoff, gbase, voff) do { _Pragma("unroll") for (int _i = 0; _i < 2; ++_i) \
;         __builtin_amdgcn_global_load_lds((const unsigned*)((const char*)(gbase) + (voff)[_i]), (LAS unsigned*)(lds + (bufoff) + ldsw + _i * 8192), 16, 0, 0); } while (0)
; #define PG8_LDA(dst, b, h) do { _Pragma("unroll") for (int m = 0; m < 4; ++m) _Pragma("unroll") for (int k = 0; k < 2; ++k) dst[m][k] = *(const LAS bf16x8*)(lds + PG8_SA(b, h) + aoff + m * 2048 + k * 1024); } while (0)
; #define PG8_LDB(dst, b, h) do { _Pragma("unroll") for (int n = 0; n < 2; ++n) _Pragma("unroll") for (int k = 0; k < 2; ++k) dst[n][k] = *(const LAS bf16x8*)(lds + PG8_SB(b, h) + boff + n * 2048 + k * 1024); } while (0)
; #define PG8_MMA(ai, bj, At, Bt) do { __builtin_amdgcn_s_setprio(1); _Pragma("unroll") for (int m = 0; m < 4; ++m) _Pragma("unroll") for (int n = 0; n < 2; ++n) _Pragma("unroll") for (int k = 0; k < 2; ++k) \
;         acc[ai][bj][m][n] = __builtin_amdgcn_mfma_f32_16x16x32_bf16(Bt[n][k], At[m][k], acc[ai][bj][m][n], 0, 0, 0); __builtin_amdgcn_s_setprio(0); } while (0)
; #define PG8_WAIT_V(n) asm volatile("s_waitcnt vmcnt(" #n ")" ::: "memory")
; #define PG8_WAIT_L(n) asm volatile("s_waitcnt lgkmcnt(" #n ")" ::: "memory")
; #define PG8_BAR __builtin_amdgcn_s_barrier()
; #define PG8_SCHED __builtin_amdgcn_sched_barrier(0)
; template <class Epi, class Sched>
; __device__ __forceinline__ void gemm_phase(LAS unsigned char* lds, const Gemm g, const Sched& S, const Epi& E) {
;     ...
;         for (int t = 0; t < nt; t += 2) {
;             const bool last = (t == nt - 2);
;             const char* a1 = cA + (size_t)(t + 1) * kstep;
;             const char* a2 = last ? nA : cA + (size_t)(t + 2) * kstep; const char* b2 = last ? nB : cB + (size_t)(t + 2) * kstep;
;             const char* a3 = a2 + kstep; const char* b3 = b2 + kstep;
;             PG8_LDB(B0, 0, 0); PG8_LDB(B1, 0, 1); PG8_SCHED; PG8_LDA(At, 0, 0); PG8_STAGE(PG8_SA(1, 1), a1 + hstep, voffA);
;             PG8_WAIT_V(8); PG8_WAIT_L(0); PG8_BAR; PG8_MMA(0, 0, At, B0); PG8_MMA(0, 1, At, B1); PG8_BAR; PG8_SCHED;
;             PG8_LDA(At, 0, 1); PG8_STAGE(PG8_SB(0, 0), b2, voffB); PG8_STAGE(PG8_SB(0, 1), b2 + hstep, voffB); PG8_STAGE(PG8_SA(0, 0), a2, voffA);
;             PG8_WAIT_V(8); PG8_WAIT_L(0); PG8_BAR; PG8_MMA(1, 0, At, B0); PG8_MMA(1, 1, At, B1); PG8_BAR; PG8_SCHED;
.LBB0_599:
	s_add_i32 s19, s17, 2
	s_add_u32 s14, s6, 0x80
	s_addc_u32 s15, s7, 0
	s_add_i32 s33, 0, 0x10000
	s_cmp_eq_u32 s12, s17
	s_cselect_b32 s15, s1, s15
	s_cselect_b32 s14, s0, s14
	s_cselect_b32 s43, s65, s16
	s_cselect_b32 s42, s64, s13
	s_add_i32 s17, 0, 0x14000
	v_add_u32_e32 v140, s33, v231
	v_add_u32_e32 v156, s17, v231
	s_waitcnt lgkmcnt(0)
	ds_read_b128 v[128:131], v140
	ds_read_b128 v[132:135], v140 offset:1024
	ds_read_b128 v[136:139], v140 offset:2048
	ds_read_b128 v[140:143], v140 offset:3072
	ds_read_b128 v[144:147], v156
	ds_read_b128 v[148:151], v156 offset:1024
	ds_read_b128 v[152:155], v156 offset:2048
	ds_read_b128 v[156:159], v156 offset:3072
	s_add_i32 m0, s29, 0xc000
	ds_read_b128 v[160:163], v232
	ds_read_b128 v[164:167], v232 offset:1024
	ds_read_b128 v[168:171], v232 offset:2048
	ds_read_b128 v[172:175], v232 offset:3072
	ds_read_b128 v[176:179], v232 offset:4096
	ds_read_b128 v[202:205], v232 offset:5120
	ds_read_b128 v[206:209], v232 offset:6144
	ds_read_b128 v[210:213], v232 offset:7168
	global_load_lds_dwordx4 v198, s[6:7]
	s_add_i32 m0, s29, 0xe000
	s_nop 0
	global_load_lds_dwordx4 v200, s[6:7]
	s_waitcnt vmcnt(8)
	s_waitcnt lgkmcnt(0)
	s_barrier
	s_setprio 1
	s_waitcnt lgkmcnt(0)
	v_mfma_f32_16x16x32_bf16 v[124:127], v[128:131], v[160:163], v[124:127]
	v_mfma_f32_16x16x32_bf16 v[120:123], v[136:139], v[160:163], v[120:123]
	v_mfma_f32_16x16x32_bf16 v[116:119], v[128:131], v[168:171], v[116:119]
	v_mfma_f32_16x16x32_bf16 v[112:115], v[136:139], v[168:171], v[112:115]
	v_mfma_f32_16x16x32_bf16 v[104:107], v[128:131], v[176:179], v[104:107]
	v_mfma_f32_16x16x32_bf16 v[96:99], v[136:139], v[176:179], v[96:99]
	v_mfma_f32_16x16x32_bf16 v[88:91], v[128:131], v[206:209], v[88:91]
	v_mfma_f32_16x16x32_bf16 v[80:83], v[136:139], v[206:209], v[80:83]
	v_mfma_f32_16x16x32_bf16 v[124:127], v[132:135], v[164:167], v[124:127]
	v_mfma_f32_16x16x32_bf16 v[120:123], v[140:143], v[164:167], v[120:123]
	v_mfma_f32_16x16x32_bf16 v[116:119], v[132:135], v[172:175], v[116:119]
	v_mfma_f32_16x16x32_bf16 v[112:115], v[140:143], v[172:175], v[112:115]
	v_mfma_f32_16x16x32_bf16 v[104:107], v[132:135], v[202:205], v[104:107]
	v_mfma_f32_16x16x32_bf16 v[96:99], v[140:143], v[202:205], v[96:99]
	v_mfma_f32_16x16x32_bf16 v[88:91], v[132:135], v[210:213], v[88:91]
	v_mfma_f32_16x16x32_bf16 v[80:83], v[140:143], v[210:213], v[80:83]
	s_setprio 0
	s_setprio 1
	v_mfma_f32_16x16x32_bf16 v[108:111], v[144:147], v[160:163], v[108:111]
	v_mfma_f32_16x16x32_bf16 v[100:103], v[152:155], v[160:163], v[100:103]
	v_mfma_f32_16x16x32_bf16 v[92:95], v[144:147], v[168:171], v[92:95]
	v_mfma_f32_16x16x32_bf16 v[84:87], v[152:155], v[168:171], v[84:87]
	v_mfma_f32_16x16x32_bf16 v[76:79], v[144:147], v[176:179], v[76:79]
	v_mfma_f32_16x16x32_bf16 v[72:75], v[152:155], v[176:179], v[72:75]
	v_mfma_f32_16x16x32_bf16 v[68:71], v[144:147], v[206:209], v[68:71]
	v_mfma_f32_16x16x32_bf16 v[64:67], v[152:155], v[206:209], v[64:67]
	v_mfma_f32_16x16x32_bf16 v[108:111], v[148:151], v[164:167], v[108:111]
	v_mfma_f32_16x16x32_bf16 v[100:103], v[156:159], v[164:167], v[100:103]
	v_mfma_f32_16x16x32_bf16 v[92:95], v[148:151], v[172:175], v[92:95]
	v_mfma_f32_16x16x32_bf16 v[84:87], v[156:159], v[172:175], v[84:87]
	v_mfma_f32_16x16x32_bf16 v[76:79], v[148:151], v[202:205], v[76:79]
	v_mfma_f32_16x16x32_bf16 v[72:75], v[156:159], v[202:205], v[72:75]
	v_mfma_f32_16x16x32_bf16 v[68:71], v[148:151], v[210:213], v[68:71]
	v_mfma_f32_16x16x32_bf16 v[64:67], v[156:159], v[210:213], v[64:67]
	s_setprio 0
	s_barrier
	s_add_i32 s33, s33, s28
	s_mov_b32 m0, s33
	ds_read_b128 v[160:163], v232 offset:16384
	ds_read_b128 v[164:167], v232 offset:17408
	ds_read_b128 v[168:171], v232 offset:18432
	ds_read_b128 v[172:175], v232 offset:19456
	ds_read_b128 v[176:179], v232 offset:20480
	ds_read_b128 v[202:205], v232 offset:21504
	ds_read_b128 v[206:209], v232 offset:22528
	ds_read_b128 v[210:213], v232 offset:23552
	global_load_lds_dwordx4 v184, s[42:43]
	s_add_i32 m0, s33, 0x2000
	s_nop 0
	global_load_lds_dwordx4 v196, s[42:43]
	s_add_u32 s42, s42, s54
	s_addc_u32 s43, s43, 0
	s_add_i32 s17, s17, s28
	s_mov_b32 m0, s17
	s_nop 0
	global_load_lds_dwordx4 v184, s[42:43]
	s_add_i32 m0, s17, 0x2000
	s_nop 0
	global_load_lds_dwordx4 v196, s[42:43]
	s_mov_b32 m0, s29
	s_nop 0
	global_load_lds_dwordx4 v192, s[14:15]
	s_mov_b32 m0, s30
	s_nop 0
	global_load_lds_dwordx4 v194, s[14:15]
	s_waitcnt vmcnt(8)
	s_waitcnt lgkmcnt(0)
	s_barrier
	s_setprio 1
	s_waitcnt lgkmcnt(0)
	v_mfma_f32_16x16x32_bf16 v[60:63], v[128:131], v[160:163], v[60:63]
	v_mfma_f32_16x16x32_bf16 v[56:59], v[136:139], v[160:163], v[56:59]
	v_mfma_f32_16x16x32_bf16 v[52:55], v[128:131], v[168:171], v[52:55]
	v_mfma_f32_16x16x32_bf16 v[48:51], v[136:139], v[168:171], v[48:51]
	v_mfma_f32_16x16x32_bf16 v[36:39], v[128:131], v[176:179], v[36:39]
	v_mfma_f32_16x16x32_bf16 v[32:35], v[136:139], v[176:179], v[32:35]
	v_mfma_f32_16x16x32_bf16 v[20:23], v[128:131], v[206:209], v[20:23]
	v_mfma_f32_16x16x32_bf16 v[16:19], v[136:139], v[206:209], v[16:19]
	v_mfma_f32_16x16x32_bf16 v[60:63], v[132:135], v[164:167], v[60:63]
	v_mfma_f32_16x16x32_bf16 v[56:59], v[140:143], v[164:167], v[56:59]
	v_mfma_f32_16x16x32_bf16 v[52:55], v[132:135], v[172:175], v[52:55]
	v_mfma_f32_16x16x32_bf16 v[48:51], v[140:143], v[172:175], v[48:51]
	v_mfma_f32_16x16x32_bf16 v[36:39], v[132:135], v[202:205], v[36:39]
	v_mfma_f32_16x16x32_bf16 v[32:35], v[140:143], v[202:205], v[32:35]
	v_mfma_f32_16x16x32_bf16 v[20:23], v[132:135], v[210:213], v[20:23]
	v_mfma_f32_16x16x32_bf16 v[16:19], v[140:143], v[210:213], v[16:19]
	s_setprio 0
	s_setprio 1
	v_mfma_f32_16x16x32_bf16 v[44:47], v[144:147], v[160:163], v[44:47]
	v_mfma_f32_16x16x32_bf16 v[40:43], v[152:155], v[160:163], v[40:43]
	v_mfma_f32_16x16x32_bf16 v[28:31], v[144:147], v[168:171], v[28:31]
	v_mfma_f32_16x16x32_bf16 v[24:27], v[152:155], v[168:171], v[24:27]
	v_mfma_f32_16x16x32_bf16 v[12:15], v[144:147], v[176:179], v[12:15]
	v_mfma_f32_16x16x32_bf16 v[8:11], v[152:155], v[176:179], v[8:11]
	v_mfma_f32_16x16x32_bf16 v[4:7], v[144:147], v[206:209], v[4:7]
	v_mfma_f32_16x16x32_bf16 v[0:3], v[152:155], v[206:209], v[0:3]
	v_mfma_f32_16x16x32_bf16 v[44:47], v[148:151], v[164:167], v[44:47]
	v_mfma_f32_16x16x32_bf16 v[40:43], v[156:159], v[164:167], v[40:43]
	v_mfma_f32_16x16x32_bf16 v[28:31], v[148:151], v[172:175], v[28:31]
	v_mfma_f32_16x16x32_bf16 v[24:27], v[156:159], v[172:175], v[24:27]
	v_mfma_f32_16x16x32_bf16 v[12:15], v[148:151], v[202:205], v[12:15]
	v_mfma_f32_16x16x32_bf16 v[8:11], v[156:159], v[202:205], v[8:11]
	v_mfma_f32_16x16x32_bf16 v[4:7], v[148:151], v[210:213], v[4:7]
	v_mfma_f32_16x16x32_bf16 v[0:3], v[156:159], v[210:213], v[0:3]
	s_setprio 0
	s_barrier
; #define PG8_STAGE(bufoff, gbase, voff) do { _Pragma("unroll") for (int _i = 0; _i < 2; ++_i) \
;         __builtin_amdgcn_global_load_lds((const unsigned*)((const char*)(gbase) + (voff)[_i]), (LAS unsigned*)(lds + (bufoff) + ldsw + _i * 8192), 16, 0, 0); } while (0)
; #define PG8_LDA(dst, b, h) do { _Pragma("unroll") for (int m = 0; m < 4; ++m) _Pragma("unroll") for (int k = 0; k < 2; ++k) dst[m][k] = *(const LAS bf16x8*)(lds + PG8_SA(b, h) + aoff + m * 2048 + k * 1024); } while (0)
; #define PG8_LDB(dst, b, h) do { _Pragma("unroll") for (int n = 0; n < 2; ++n) _Pragma("unroll") for (int k = 0; k < 2; ++k) dst[n][k] = *(const LAS bf16x8*)(lds + PG8_SB(b, h) + boff + n * 2048 + k * 1024); } while (0)
; #define PG8_MMA(ai, bj, At, Bt) do { __builtin_amdgcn_s_setprio(1); _Pragma("unroll") for (int m = 0; m < 4; ++m) _Pragma("unroll") for (int n = 0; n < 2; ++n) _Pragma("unroll") for (int k = 0; k < 2; ++k) \
;         acc[ai][bj][m][n] = __builtin_amdgcn_mfma_f32_16x16x32_bf16(Bt[n][k], At[m][k], acc[ai][bj][m][n], 0, 0, 0); __builtin_amdgcn_s_setprio(0); } while (0)
; #define PG8_WAIT_V(n) asm volatile("s_waitcnt vmcnt(" #n ")" ::: "memory")
; #define PG8_WAIT_L(n) asm volatile("s_waitcnt lgkmcnt(" #n ")" ::: "memory")
; #define PG8_BAR __builtin_amdgcn_s_barrier()
; #define PG8_SCHED __builtin_amdgcn_sched_barrier(0)
; template <class Epi, class Sched>
; __device__ __forceinline__ void gemm_phase(LAS unsigned char* lds, const Gemm g, const Sched& S, const Epi& E) {
;     ...
;             PG8_LDB(B0, 1, 0); PG8_LDB(B1, 1, 1); PG8_SCHED; PG8_LDA(At, 1, 0); PG8_STAGE(PG8_SA(0, 1), a2 + hstep, voffA);
;             PG8_WAIT_V(8); PG8_WAIT_L(0); PG8_BAR; PG8_MMA(0, 0, At, B0); PG8_MMA(0, 1, At, B1); PG8_BAR; PG8_SCHED;
;             PG8_LDA(At, 1, 1); PG8_STAGE(PG8_SB(1, 0), b3, voffB); PG8_STAGE(PG8_SB(1, 1), b3 + hstep, voffB); PG8_STAGE(PG8_SA(1, 0), a3, voffA);
;             PG8_WAIT_V(8); PG8_WAIT_L(0); PG8_BAR; PG8_MMA(1, 0, At, B0); PG8_MMA(1, 1, At, B1); PG8_BAR; PG8_SCHED;
;         }
	s_add_i32 s17, 0, 0x18000
	s_add_i32 s33, 0, 0x1c000
	v_add_u32_e32 v140, s17, v231
	v_add_u32_e32 v156, s33, v231
	ds_read_b128 v[128:131], v140
	ds_read_b128 v[132:135], v140 offset:1024
	ds_read_b128 v[136:139], v140 offset:2048
	ds_read_b128 v[140:143], v140 offset:3072
	ds_read_b128 v[144:147], v156
	ds_read_b128 v[148:151], v156 offset:1024
	ds_read_b128 v[152:155], v156 offset:2048
	ds_read_b128 v[156:159], v156 offset:3072
	s_add_u32 s14, s14, s54
	s_addc_u32 s15, s15, 0
	s_mov_b32 m0, s31
	ds_read_b128 v[160:163], v232 offset:32768
	ds_read_b128 v[164:167], v232 offset:33792
	ds_read_b128 v[168:171], v232 offset:34816
	ds_read_b128 v[172:175], v232 offset:35840
	ds_read_b128 v[176:179], v232 offset:36864
	ds_read_b128 v[202:205], v232 offset:37888
	ds_read_b128 v[206:209], v232 offset:38912
	ds_read_b128 v[210:213], v232 offset:39936
	global_load_lds_dwordx4 v192, s[14:15]
	s_mov_b32 m0, s34
	s_nop 0
	global_load_lds_dwordx4 v194, s[14:15]
	s_waitcnt vmcnt(8)
	s_waitcnt lgkmcnt(0)
	s_barrier
	s_setprio 1
	s_waitcnt lgkmcnt(0)
	v_mfma_f32_16x16x32_bf16 v[124:127], v[128:131], v[160:163], v[124:127]
	v_mfma_f32_16x16x32_bf16 v[120:123], v[136:139], v[160:163], v[120:123]
	v_mfma_f32_16x16x32_bf16 v[116:119], v[128:131], v[168:171], v[116:119]
	v_mfma_f32_16x16x32_bf16 v[112:115], v[136:139], v[168:171], v[112:115]
	v_mfma_f32_16x16x32_bf16 v[104:107], v[128:131], v[176:179], v[104:107]
	v_mfma_f32_16x16x32_bf16 v[96:99], v[136:139], v[176:179], v[96:99]
	v_mfma_f32_16x16x32_bf16 v[88:91], v[128:131], v[206:209], v[88:91]
	v_mfma_f32_16x16x32_bf16 v[80:83], v[136:139], v[206:209], v[80:83]
	v_mfma_f32_16x16x32_bf16 v[124:127], v[132:135], v[164:167], v[124:127]
	v_mfma_f32_16x16x32_bf16 v[120:123], v[140:143], v[164:167], v[120:123]
	v_mfma_f32_16x16x32_bf16 v[116:119], v[132:135], v[172:175], v[116:119]
	v_mfma_f32_16x16x32_bf16 v[112:115], v[140:143], v[172:175], v[112:115]
	v_mfma_f32_16x16x32_bf16 v[104:107], v[132:135], v[202:205], v[104:107]
	v_mfma_f32_16x16x32_bf16 v[96:99], v[140:143], v[202:205], v[96:99]
	v_mfma_f32_16x16x32_bf16 v[88:91], v[132:135], v[210:213], v[88:91]
	v_mfma_f32_16x16x32_bf16 v[80:83], v[140:143], v[210:213], v[80:83]
	s_setprio 0
	s_setprio 1
	v_mfma_f32_16x16x32_bf16 v[108:111], v[144:147], v[160:163], v[108:111]
	v_mfma_f32_16x16x32_bf16 v[100:103], v[152:155], v[160:163], v[100:103]
	v_mfma_f32_16x16x32_bf16 v[92:95], v[144:147], v[168:171], v[92:95]
	v_mfma_f32_16x16x32_bf16 v[84:87], v[152:155], v[168:171], v[84:87]
	v_mfma_f32_16x16x32_bf16 v[76:79], v[144:147], v[176:179], v[76:79]
	v_mfma_f32_16x16x32_bf16 v[72:75], v[152:155], v[176:179], v[72:75]
	v_mfma_f32_16x16x32_bf16 v[68:71], v[144:147], v[206:209], v[68:71]
	v_mfma_f32_16x16x32_bf16 v[64:67], v[152:155], v[206:209], v[64:67]
	v_mfma_f32_16x16x32_bf16 v[108:111], v[148:151], v[164:167], v[108:111]
	v_mfma_f32_16x16x32_bf16 v[100:103], v[156:159], v[164:167], v[100:103]
	v_mfma_f32_16x16x32_bf16 v[92:95], v[148:151], v[172:175], v[92:95]
	v_mfma_f32_16x16x32_bf16 v[84:87], v[156:159], v[172:175], v[84:87]
	v_mfma_f32_16x16x32_bf16 v[76:79], v[148:151], v[202:205], v[76:79]
	v_mfma_f32_16x16x32_bf16 v[72:75], v[156:159], v[202:205], v[72:75]
	v_mfma_f32_16x16x32_bf16 v[68:71], v[148:151], v[210:213], v[68:71]
	v_mfma_f32_16x16x32_bf16 v[64:67], v[156:159], v[210:213], v[64:67]
	s_setprio 0
	s_barrier
	s_sub_u32 s42, s42, s54
	s_subb_u32 s43, s43, 0
	s_add_u32 s42, s42, 0x80
	s_addc_u32 s43, s43, 0
	s_add_i32 m0, s17, s28
	ds_read_b128 v[160:163], v232 offset:49152
	ds_read_b128 v[164:167], v232 offset:50176
	ds_read_b128 v[168:171], v232 offset:51200
	ds_read_b128 v[172:175], v232 offset:52224
	ds_read_b128 v[176:179], v232 offset:53248
	ds_read_b128 v[202:205], v232 offset:54272
	ds_read_b128 v[206:209], v232 offset:55296
	ds_read_b128 v[210:213], v232 offset:56320
	global_load_lds_dwordx4 v184, s[42:43]
	s_add_i32 m0, m0, 0x2000
	s_nop 0
	global_load_lds_dwordx4 v196, s[42:43]
	s_add_u32 s42, s42, s54
	s_addc_u32 s43, s43, 0
	s_add_i32 m0, s33, s28
	s_nop 0
	global_load_lds_dwordx4 v184, s[42:43]
	s_add_i32 m0, m0, 0x2000
	s_nop 0
	global_load_lds_dwordx4 v196, s[42:43]
	s_sub_u32 s14, s14, s54
	s_subb_u32 s15, s15, 0
	s_add_u32 s14, s14, 0x80
	s_addc_u32 s15, s15, 0
	s_mov_b32 m0, s66
	s_nop 0
	global_load_lds_dwordx4 v192, s[14:15]
	s_mov_b32 m0, s67
	s_nop 0
	global_load_lds_dwordx4 v194, s[14:15]
	s_waitcnt vmcnt(8)
	s_waitcnt lgkmcnt(0)
	s_barrier
	s_setprio 1
	s_waitcnt lgkmcnt(0)
	v_mfma_f32_16x16x32_bf16 v[60:63], v[128:131], v[160:163], v[60:63]
	v_mfma_f32_16x16x32_bf16 v[56:59], v[136:139], v[160:163], v[56:59]
	v_mfma_f32_16x16x32_bf16 v[52:55], v[128:131], v[168:171], v[52:55]
	v_mfma_f32_16x16x32_bf16 v[48:51], v[136:139], v[168:171], v[48:51]
	v_mfma_f32_16x16x32_bf16 v[36:39], v[128:131], v[176:179], v[36:39]
	v_mfma_f32_16x16x32_bf16 v[32:35], v[136:139], v[176:179], v[32:35]
	v_mfma_f32_16x16x32_bf16 v[20:23], v[128:131], v[206:209], v[20:23]
	v_mfma_f32_16x16x32_bf16 v[16:19], v[136:139], v[206:209], v[16:19]
	v_mfma_f32_16x16x32_bf16 v[60:63], v[132:135], v[164:167], v[60:63]
	v_mfma_f32_16x16x32_bf16 v[56:59], v[140:143], v[164:167], v[56:59]
	v_mfma_f32_16x16x32_bf16 v[52:55], v[132:135], v[172:175], v[52:55]
	v_mfma_f32_16x16x32_bf16 v[48:51], v[140:143], v[172:175], v[48:51]
	v_mfma_f32_16x16x32_bf16 v[36:39], v[132:135], v[202:205], v[36:39]
	v_mfma_f32_16x16x32_bf16 v[32:35], v[140:143], v[202:205], v[32:35]
	v_mfma_f32_16x16x32_bf16 v[20:23], v[132:135], v[210:213], v[20:23]
	v_mfma_f32_16x16x32_bf16 v[16:19], v[140:143], v[210:213], v[16:19]
	s_setprio 0
	s_setprio 1
	v_mfma_f32_16x16x32_bf16 v[44:47], v[144:147], v[160:163], v[44:47]
	v_mfma_f32_16x16x32_bf16 v[40:43], v[152:155], v[160:163], v[40:43]
	v_mfma_f32_16x16x32_bf16 v[28:31], v[144:147], v[168:171], v[28:31]
	v_mfma_f32_16x16x32_bf16 v[24:27], v[152:155], v[168:171], v[24:27]
	v_mfma_f32_16x16x32_bf16 v[12:15], v[144:147], v[176:179], v[12:15]
	v_mfma_f32_16x16x32_bf16 v[8:11], v[152:155], v[176:179], v[8:11]
	v_mfma_f32_16x16x32_bf16 v[4:7], v[144:147], v[206:209], v[4:7]
	v_mfma_f32_16x16x32_bf16 v[0:3], v[152:155], v[206:209], v[0:3]
	v_mfma_f32_16x16x32_bf16 v[44:47], v[148:151], v[164:167], v[44:47]
	v_mfma_f32_16x16x32_bf16 v[40:43], v[156:159], v[164:167], v[40:43]
	v_mfma_f32_16x16x32_bf16 v[28:31], v[148:151], v[172:175], v[28:31]
	v_mfma_f32_16x16x32_bf16 v[24:27], v[156:159], v[172:175], v[24:27]
	v_mfma_f32_16x16x32_bf16 v[12:15], v[148:151], v[202:205], v[12:15]
	v_mfma_f32_16x16x32_bf16 v[8:11], v[156:159], v[202:205], v[8:11]
	v_mfma_f32_16x16x32_bf16 v[4:7], v[148:151], v[210:213], v[4:7]
	v_mfma_f32_16x16x32_bf16 v[0:3], v[156:159], v[210:213], v[0:3]
	s_setprio 0
	s_barrier
	s_add_u32 s6, s6, 0x100
	s_addc_u32 s7, s7, 0
	s_add_u32 s13, s13, 0x100
	s_addc_u32 s16, s16, 0
	s_cmp_ge_u32 s19, s8
	s_mov_b32 s17, s19
	s_cbranch_scc0 .LBB0_599
	s_and_b64 vcc, exec, s[62:63]
	s_cbranch_vccz .LBB0_602
	s_barrier

; #define PG8_STAGE(bufoff, gbase, voff) do { _Pragma("unroll") for (int _i = 0; _i < 2; ++_i) \
;         __builtin_amdgcn_global_load_lds((const unsigned*)((const char*)(gbase) + (voff)[_i]), (LAS unsigned*)(lds + (bufoff) + ldsw + _i * 8192), 16, 0, 0); } while (0)
; #define PG8_LDA(dst, b, h) do { _Pragma("unroll") for (int m = 0; m < 4; ++m) _Pragma("unroll") for (int k = 0; k < 2; ++k) dst[m][k] = *(const LAS bf16x8*)(lds + PG8_SA(b, h) + aoff + m * 2048 + k * 1024); } while (0)
; #define PG8_LDB(dst, b, h) do { _Pragma("unroll") for (int n = 0; n < 2; ++n) _Pragma("unroll") for (int k = 0; k < 2; ++k) dst[n][k] = *(const LAS bf16x8*)(lds + PG8_SB(b, h) + boff + n * 2048 + k * 1024); } while (0)
; #define PG8_MMA(ai, bj, At, Bt) do { __builtin_amdgcn_s_setprio(1); _Pragma("unroll") for (int m = 0; m < 4; ++m) _Pragma("unroll") for (int n = 0; n < 2; ++n) _Pragma("unroll") for (int k = 0; k < 2; ++k) \
;         acc[ai][bj][m][n] = __builtin_amdgcn_mfma_f32_16x16x32_bf16(Bt[n][k], At[m][k], acc[ai][bj][m][n], 0, 0, 0); __builtin_amdgcn_s_setprio(0); } while (0)
; #define PG8_WAIT_V(n) asm volatile("s_waitcnt vmcnt(" #n ")" ::: "memory")
; #define PG8_WAIT_L(n) asm volatile("s_waitcnt lgkmcnt(" #n ")" ::: "memory")
; #define PG8_BAR __builtin_amdgcn_s_barrier()
; #define PG8_SCHED __builtin_amdgcn_sched_barrier(0)
; template <class Epi, class Sched>
; __device__ __forceinline__ void gemm_phase(LAS unsigned char* lds, const Gemm g, const Sched& S, const Epi& E) {
;     ...
;             const char* a1 = cA + (size_t)(t + 1) * kstep;
;             const char* a2 = last ? nA : cA + (size_t)(t + 2) * kstep; const char* b2 = last ? nB : cB + (size_t)(t + 2) * kstep;
;             const char* a3 = a2 + kstep; const char* b3 = b2 + kstep;
;             PG8_LDB(B0, 0, 0); PG8_LDB(B1, 0, 1); PG8_SCHED; PG8_LDA(At, 0, 0); PG8_STAGE(PG8_SA(1, 1), a1 + hstep, voffA);
;             PG8_WAIT_V(8); PG8_WAIT_L(0); PG8_BAR; PG8_MMA(0, 0, At, B0); PG8_MMA(0, 1, At, B1); PG8_BAR; PG8_SCHED;
;             PG8_LDA(At, 0, 1); PG8_STAGE(PG8_SB(0, 0), b2, voffB); PG8_STAGE(PG8_SB(0, 1), b2 + hstep, voffB); PG8_STAGE(PG8_SA(0, 0), a2, voffA);
;             PG8_WAIT_V(8); PG8_WAIT_L(0); PG8_BAR; PG8_MMA(1, 0, At, B0); PG8_MMA(1, 1, At, B1); PG8_BAR; PG8_SCHED;
.LBB0_744:
	s_add_u32 s24, s22, 0xfffc0080
	s_addc_u32 s25, s23, -1
	s_add_i32 s49, 0, 0x10000
	s_cmp_eq_u32 s48, 12
	s_cselect_b32 s27, s15, s25
	s_cselect_b32 s26, s44, s24
	s_cselect_b32 s25, s17, s47
	s_cselect_b32 s24, s45, s46
	s_add_i32 s52, 0, 0x14000
	v_add_u32_e32 v140, s49, v162
	v_add_u32_e32 v158, s52, v162
	ds_read_b128 v[128:131], v140
	ds_read_b128 v[132:135], v140 offset:1024
	ds_read_b128 v[136:139], v140 offset:2048
	ds_read_b128 v[140:143], v140 offset:3072
	ds_read_b128 v[154:157], v158
	ds_read_b128 v[164:167], v158 offset:1024
	ds_read_b128 v[168:171], v158 offset:2048
	ds_read_b128 v[172:175], v158 offset:3072
	s_add_i32 m0, s28, 0xc000
	ds_read_b128 v[176:179], v163
	ds_read_b128 v[192:195], v163 offset:1024
	ds_read_b128 v[196:199], v163 offset:2048
	ds_read_b128 v[200:203], v163 offset:3072
	ds_read_b128 v[204:207], v163 offset:4096
	ds_read_b128 v[208:211], v163 offset:5120
	ds_read_b128 v[212:215], v163 offset:6144
	ds_read_b128 v[230:233], v163 offset:7168
	global_load_lds_dwordx4 v150, s[22:23]
	s_add_i32 m0, s28, 0xe000
	s_nop 0
	global_load_lds_dwordx4 v152, s[22:23]
	s_waitcnt vmcnt(8)
	s_waitcnt lgkmcnt(0)
	s_barrier
	s_setprio 1
	s_waitcnt lgkmcnt(0)
	v_mfma_f32_16x16x32_bf16 v[124:127], v[128:131], v[176:179], v[124:127]
	v_mfma_f32_16x16x32_bf16 v[120:123], v[136:139], v[176:179], v[120:123]
	v_mfma_f32_16x16x32_bf16 v[108:111], v[128:131], v[196:199], v[108:111]
	v_mfma_f32_16x16x32_bf16 v[104:107], v[136:139], v[196:199], v[104:107]
	v_mfma_f32_16x16x32_bf16 v[92:95], v[128:131], v[204:207], v[92:95]
	v_mfma_f32_16x16x32_bf16 v[88:91], v[136:139], v[204:207], v[88:91]
	v_mfma_f32_16x16x32_bf16 v[76:79], v[128:131], v[212:215], v[76:79]
	v_mfma_f32_16x16x32_bf16 v[72:75], v[136:139], v[212:215], v[72:75]
	v_mfma_f32_16x16x32_bf16 v[124:127], v[132:135], v[192:195], v[124:127]
	v_mfma_f32_16x16x32_bf16 v[120:123], v[140:143], v[192:195], v[120:123]
	v_mfma_f32_16x16x32_bf16 v[108:111], v[132:135], v[200:203], v[108:111]
	v_mfma_f32_16x16x32_bf16 v[104:107], v[140:143], v[200:203], v[104:107]
	v_mfma_f32_16x16x32_bf16 v[92:95], v[132:135], v[208:211], v[92:95]
	v_mfma_f32_16x16x32_bf16 v[88:91], v[140:143], v[208:211], v[88:91]
	v_mfma_f32_16x16x32_bf16 v[76:79], v[132:135], v[230:233], v[76:79]
	v_mfma_f32_16x16x32_bf16 v[72:75], v[140:143], v[230:233], v[72:75]
	s_setprio 0
	s_setprio 1
	v_mfma_f32_16x16x32_bf16 v[112:115], v[154:157], v[176:179], v[112:115]
	v_mfma_f32_16x16x32_bf16 v[116:119], v[168:171], v[176:179], v[116:119]
	v_mfma_f32_16x16x32_bf16 v[96:99], v[154:157], v[196:199], v[96:99]
	v_mfma_f32_16x16x32_bf16 v[100:103], v[168:171], v[196:199], v[100:103]
	v_mfma_f32_16x16x32_bf16 v[80:83], v[154:157], v[204:207], v[80:83]
	v_mfma_f32_16x16x32_bf16 v[84:87], v[168:171], v[204:207], v[84:87]
	v_mfma_f32_16x16x32_bf16 v[64:67], v[154:157], v[212:215], v[64:67]
	v_mfma_f32_16x16x32_bf16 v[68:71], v[168:171], v[212:215], v[68:71]
	v_mfma_f32_16x16x32_bf16 v[112:115], v[164:167], v[192:195], v[112:115]
	v_mfma_f32_16x16x32_bf16 v[116:119], v[172:175], v[192:195], v[116:119]
	v_mfma_f32_16x16x32_bf16 v[96:99], v[164:167], v[200:203], v[96:99]
	v_mfma_f32_16x16x32_bf16 v[100:103], v[172:175], v[200:203], v[100:103]
	v_mfma_f32_16x16x32_bf16 v[80:83], v[164:167], v[208:211], v[80:83]
	v_mfma_f32_16x16x32_bf16 v[84:87], v[172:175], v[208:211], v[84:87]
	v_mfma_f32_16x16x32_bf16 v[64:67], v[164:167], v[230:233], v[64:67]
	v_mfma_f32_16x16x32_bf16 v[68:71], v[172:175], v[230:233], v[68:71]
	s_setprio 0
	s_barrier
	s_add_i32 s49, s49, s8
	s_mov_b32 m0, s49
	ds_read_b128 v[176:179], v163 offset:16384
	ds_read_b128 v[192:195], v163 offset:17408
	ds_read_b128 v[196:199], v163 offset:18432
	ds_read_b128 v[200:203], v163 offset:19456
	ds_read_b128 v[204:207], v163 offset:20480
	ds_read_b128 v[208:211], v163 offset:21504
	ds_read_b128 v[212:215], v163 offset:22528
	ds_read_b128 v[230:233], v163 offset:23552
	global_load_lds_dwordx4 v184, s[24:25]
	s_add_i32 m0, s49, 0x2000
	s_add_u32 s50, s24, 0x40000
	s_addc_u32 s51, s25, 0
	s_add_i32 s49, s52, s8
	global_load_lds_dwordx4 v144, s[24:25]
	s_mov_b32 m0, s49
	s_nop 0
	global_load_lds_dwordx4 v184, s[50:51]
	s_add_i32 m0, s49, 0x2000
	s_nop 0
	global_load_lds_dwordx4 v144, s[50:51]
	s_mov_b32 m0, s28
	s_nop 0
	global_load_lds_dwordx4 v148, s[26:27]
	s_mov_b32 m0, s29
	s_nop 0
	global_load_lds_dwordx4 v146, s[26:27]
	s_waitcnt vmcnt(8)
	s_waitcnt lgkmcnt(0)
	s_barrier
	s_setprio 1
	s_waitcnt lgkmcnt(0)
	v_mfma_f32_16x16x32_bf16 v[60:63], v[128:131], v[176:179], v[60:63]
	v_mfma_f32_16x16x32_bf16 v[56:59], v[136:139], v[176:179], v[56:59]
	v_mfma_f32_16x16x32_bf16 v[44:47], v[128:131], v[196:199], v[44:47]
	v_mfma_f32_16x16x32_bf16 v[40:43], v[136:139], v[196:199], v[40:43]
	v_mfma_f32_16x16x32_bf16 v[28:31], v[128:131], v[204:207], v[28:31]
	v_mfma_f32_16x16x32_bf16 v[24:27], v[136:139], v[204:207], v[24:27]
	v_mfma_f32_16x16x32_bf16 v[12:15], v[128:131], v[212:215], v[12:15]
	v_mfma_f32_16x16x32_bf16 v[8:11], v[136:139], v[212:215], v[8:11]
	v_mfma_f32_16x16x32_bf16 v[60:63], v[132:135], v[192:195], v[60:63]
	v_mfma_f32_16x16x32_bf16 v[56:59], v[140:143], v[192:195], v[56:59]
	v_mfma_f32_16x16x32_bf16 v[44:47], v[132:135], v[200:203], v[44:47]
	v_mfma_f32_16x16x32_bf16 v[40:43], v[140:143], v[200:203], v[40:43]
	v_mfma_f32_16x16x32_bf16 v[28:31], v[132:135], v[208:211], v[28:31]
	v_mfma_f32_16x16x32_bf16 v[24:27], v[140:143], v[208:211], v[24:27]
	v_mfma_f32_16x16x32_bf16 v[12:15], v[132:135], v[230:233], v[12:15]
	v_mfma_f32_16x16x32_bf16 v[8:11], v[140:143], v[230:233], v[8:11]
	s_setprio 0
	s_setprio 1
	v_mfma_f32_16x16x32_bf16 v[48:51], v[154:157], v[176:179], v[48:51]
	v_mfma_f32_16x16x32_bf16 v[52:55], v[168:171], v[176:179], v[52:55]
	v_mfma_f32_16x16x32_bf16 v[32:35], v[154:157], v[196:199], v[32:35]
	v_mfma_f32_16x16x32_bf16 v[36:39], v[168:171], v[196:199], v[36:39]
	v_mfma_f32_16x16x32_bf16 v[16:19], v[154:157], v[204:207], v[16:19]
	v_mfma_f32_16x16x32_bf16 v[20:23], v[168:171], v[204:207], v[20:23]
	v_mfma_f32_16x16x32_bf16 v[0:3], v[154:157], v[212:215], v[0:3]
	v_mfma_f32_16x16x32_bf16 v[4:7], v[168:171], v[212:215], v[4:7]
	v_mfma_f32_16x16x32_bf16 v[48:51], v[164:167], v[192:195], v[48:51]
	v_mfma_f32_16x16x32_bf16 v[52:55], v[172:175], v[192:195], v[52:55]
	v_mfma_f32_16x16x32_bf16 v[32:35], v[164:167], v[200:203], v[32:35]
	v_mfma_f32_16x16x32_bf16 v[36:39], v[172:175], v[200:203], v[36:39]
	v_mfma_f32_16x16x32_bf16 v[16:19], v[164:167], v[208:211], v[16:19]
	v_mfma_f32_16x16x32_bf16 v[20:23], v[172:175], v[208:211], v[20:23]
	v_mfma_f32_16x16x32_bf16 v[0:3], v[164:167], v[230:233], v[0:3]
	v_mfma_f32_16x16x32_bf16 v[4:7], v[172:175], v[230:233], v[4:7]
	s_setprio 0
	s_barrier
; #define PG8_STAGE(bufoff, gbase, voff) do { _Pragma("unroll") for (int _i = 0; _i < 2; ++_i) \
;         __builtin_amdgcn_global_load_lds((const unsigned*)((const char*)(gbase) + (voff)[_i]), (LAS unsigned*)(lds + (bufoff) + ldsw + _i * 8192), 16, 0, 0); } while (0)
; #define PG8_LDA(dst, b, h) do { _Pragma("unroll") for (int m = 0; m < 4; ++m) _Pragma("unroll") for (int k = 0; k < 2; ++k) dst[m][k] = *(const LAS bf16x8*)(lds + PG8_SA(b, h) + aoff + m * 2048 + k * 1024); } while (0)
; #define PG8_LDB(dst, b, h) do { _Pragma("unroll") for (int n = 0; n < 2; ++n) _Pragma("unroll") for (int k = 0; k < 2; ++k) dst[n][k] = *(const LAS bf16x8*)(lds + PG8_SB(b, h) + boff + n * 2048 + k * 1024); } while (0)
; #define PG8_MMA(ai, bj, At, Bt) do { __builtin_amdgcn_s_setprio(1); _Pragma("unroll") for (int m = 0; m < 4; ++m) _Pragma("unroll") for (int n = 0; n < 2; ++n) _Pragma("unroll") for (int k = 0; k < 2; ++k) \
;         acc[ai][bj][m][n] = __builtin_amdgcn_mfma_f32_16x16x32_bf16(Bt[n][k], At[m][k], acc[ai][bj][m][n], 0, 0, 0); __builtin_amdgcn_s_setprio(0); } while (0)
; #define PG8_WAIT_V(n) asm volatile("s_waitcnt vmcnt(" #n ")" ::: "memory")
; #define PG8_WAIT_L(n) asm volatile("s_waitcnt lgkmcnt(" #n ")" ::: "memory")
; #define PG8_BAR __builtin_amdgcn_s_barrier()
; #define PG8_SCHED __builtin_amdgcn_sched_barrier(0)
; template <class Epi, class Sched>
; __device__ __forceinline__ void gemm_phase(LAS unsigned char* lds, const Gemm g, const Sched& S, const Epi& E) {
;     ...
;             PG8_LDB(B0, 1, 0); PG8_LDB(B1, 1, 1); PG8_SCHED; PG8_LDA(At, 1, 0); PG8_STAGE(PG8_SA(0, 1), a2 + hstep, voffA);
;             PG8_WAIT_V(8); PG8_WAIT_L(0); PG8_BAR; PG8_MMA(0, 0, At, B0); PG8_MMA(0, 1, At, B1); PG8_BAR; PG8_SCHED;
;             PG8_LDA(At, 1, 1); PG8_STAGE(PG8_SB(1, 0), b3, voffB); PG8_STAGE(PG8_SB(1, 1), b3 + hstep, voffB); PG8_STAGE(PG8_SA(1, 0), a3, voffA);
;             PG8_WAIT_V(8); PG8_WAIT_L(0); PG8_BAR; PG8_MMA(1, 0, At, B0); PG8_MMA(1, 1, At, B1); PG8_BAR; PG8_SCHED;
;         }
	s_add_i32 s49, 0, 0x18000
	s_add_i32 s50, 0, 0x1c000
	v_add_u32_e32 v140, s49, v162
	v_add_u32_e32 v172, s50, v162
	ds_read_b128 v[128:131], v140
	ds_read_b128 v[132:135], v140 offset:1024
	ds_read_b128 v[136:139], v140 offset:2048
	ds_read_b128 v[140:143], v140 offset:3072
	ds_read_b128 v[154:157], v172
	ds_read_b128 v[164:167], v172 offset:1024
	ds_read_b128 v[168:171], v172 offset:2048
	ds_read_b128 v[172:175], v172 offset:3072
	s_add_u32 s26, s26, 0x40000
	s_addc_u32 s27, s27, 0
	s_mov_b32 m0, s30
	ds_read_b128 v[176:179], v163 offset:32768
	ds_read_b128 v[192:195], v163 offset:33792
	ds_read_b128 v[196:199], v163 offset:34816
	ds_read_b128 v[200:203], v163 offset:35840
	ds_read_b128 v[204:207], v163 offset:36864
	ds_read_b128 v[208:211], v163 offset:37888
	ds_read_b128 v[212:215], v163 offset:38912
	ds_read_b128 v[230:233], v163 offset:39936
	global_load_lds_dwordx4 v148, s[26:27]
	s_mov_b32 m0, s31
	s_nop 0
	global_load_lds_dwordx4 v146, s[26:27]
	s_waitcnt vmcnt(8)
	s_waitcnt lgkmcnt(0)
	s_barrier
	s_setprio 1
	s_waitcnt lgkmcnt(0)
	v_mfma_f32_16x16x32_bf16 v[124:127], v[128:131], v[176:179], v[124:127]
	v_mfma_f32_16x16x32_bf16 v[120:123], v[136:139], v[176:179], v[120:123]
	v_mfma_f32_16x16x32_bf16 v[108:111], v[128:131], v[196:199], v[108:111]
	v_mfma_f32_16x16x32_bf16 v[104:107], v[136:139], v[196:199], v[104:107]
	v_mfma_f32_16x16x32_bf16 v[92:95], v[128:131], v[204:207], v[92:95]
	v_mfma_f32_16x16x32_bf16 v[88:91], v[136:139], v[204:207], v[88:91]
	v_mfma_f32_16x16x32_bf16 v[76:79], v[128:131], v[212:215], v[76:79]
	v_mfma_f32_16x16x32_bf16 v[72:75], v[136:139], v[212:215], v[72:75]
	v_mfma_f32_16x16x32_bf16 v[124:127], v[132:135], v[192:195], v[124:127]
	v_mfma_f32_16x16x32_bf16 v[120:123], v[140:143], v[192:195], v[120:123]
	v_mfma_f32_16x16x32_bf16 v[108:111], v[132:135], v[200:203], v[108:111]
	v_mfma_f32_16x16x32_bf16 v[104:107], v[140:143], v[200:203], v[104:107]
	v_mfma_f32_16x16x32_bf16 v[92:95], v[132:135], v[208:211], v[92:95]
	v_mfma_f32_16x16x32_bf16 v[88:91], v[140:143], v[208:211], v[88:91]
	v_mfma_f32_16x16x32_bf16 v[76:79], v[132:135], v[230:233], v[76:79]
	v_mfma_f32_16x16x32_bf16 v[72:75], v[140:143], v[230:233], v[72:75]
	s_setprio 0
	s_setprio 1
	v_mfma_f32_16x16x32_bf16 v[112:115], v[154:157], v[176:179], v[112:115]
	v_mfma_f32_16x16x32_bf16 v[116:119], v[168:171], v[176:179], v[116:119]
	v_mfma_f32_16x16x32_bf16 v[96:99], v[154:157], v[196:199], v[96:99]
	v_mfma_f32_16x16x32_bf16 v[100:103], v[168:171], v[196:199], v[100:103]
	v_mfma_f32_16x16x32_bf16 v[80:83], v[154:157], v[204:207], v[80:83]
	v_mfma_f32_16x16x32_bf16 v[84:87], v[168:171], v[204:207], v[84:87]
	v_mfma_f32_16x16x32_bf16 v[64:67], v[154:157], v[212:215], v[64:67]
	v_mfma_f32_16x16x32_bf16 v[68:71], v[168:171], v[212:215], v[68:71]
	v_mfma_f32_16x16x32_bf16 v[112:115], v[164:167], v[192:195], v[112:115]
	v_mfma_f32_16x16x32_bf16 v[116:119], v[172:175], v[192:195], v[116:119]
	v_mfma_f32_16x16x32_bf16 v[96:99], v[164:167], v[200:203], v[96:99]
	v_mfma_f32_16x16x32_bf16 v[100:103], v[172:175], v[200:203], v[100:103]
	v_mfma_f32_16x16x32_bf16 v[80:83], v[164:167], v[208:211], v[80:83]
	v_mfma_f32_16x16x32_bf16 v[84:87], v[172:175], v[208:211], v[84:87]
	v_mfma_f32_16x16x32_bf16 v[64:67], v[164:167], v[230:233], v[64:67]
	v_mfma_f32_16x16x32_bf16 v[68:71], v[172:175], v[230:233], v[68:71]
	s_setprio 0
	s_barrier
	s_add_u32 s24, s24, 0x80
	s_addc_u32 s25, s25, 0
	s_add_i32 m0, s49, s8
	ds_read_b128 v[176:179], v163 offset:49152
	ds_read_b128 v[192:195], v163 offset:50176
	ds_read_b128 v[196:199], v163 offset:51200
	ds_read_b128 v[200:203], v163 offset:52224
	ds_read_b128 v[204:207], v163 offset:53248
	ds_read_b128 v[208:211], v163 offset:54272
	ds_read_b128 v[212:215], v163 offset:55296
	ds_read_b128 v[230:233], v163 offset:56320
	global_load_lds_dwordx4 v184, s[24:25]
	s_add_i32 m0, m0, 0x2000
	s_nop 0
	global_load_lds_dwordx4 v144, s[24:25]
	s_add_u32 s24, s24, 0x40000
	s_addc_u32 s25, s25, 0
	s_add_i32 m0, s50, s8
	s_nop 0
	global_load_lds_dwordx4 v184, s[24:25]
	s_add_i32 m0, m0, 0x2000
	s_nop 0
	global_load_lds_dwordx4 v144, s[24:25]
	s_add_u32 s26, s26, 0xfffc0080
	s_addc_u32 s27, s27, -1
	s_mov_b32 m0, s36
	s_nop 0
	global_load_lds_dwordx4 v148, s[26:27]
	s_mov_b32 m0, s37
	s_nop 0
	global_load_lds_dwordx4 v146, s[26:27]
	s_waitcnt vmcnt(8)
	s_waitcnt lgkmcnt(0)
	s_barrier
	s_setprio 1
	s_waitcnt lgkmcnt(0)
	v_mfma_f32_16x16x32_bf16 v[60:63], v[128:131], v[176:179], v[60:63]
	v_mfma_f32_16x16x32_bf16 v[56:59], v[136:139], v[176:179], v[56:59]
	v_mfma_f32_16x16x32_bf16 v[44:47], v[128:131], v[196:199], v[44:47]
	v_mfma_f32_16x16x32_bf16 v[40:43], v[136:139], v[196:199], v[40:43]
	v_mfma_f32_16x16x32_bf16 v[28:31], v[128:131], v[204:207], v[28:31]
	v_mfma_f32_16x16x32_bf16 v[24:27], v[136:139], v[204:207], v[24:27]
	v_mfma_f32_16x16x32_bf16 v[12:15], v[128:131], v[212:215], v[12:15]
	v_mfma_f32_16x16x32_bf16 v[8:11], v[136:139], v[212:215], v[8:11]
	v_mfma_f32_16x16x32_bf16 v[60:63], v[132:135], v[192:195], v[60:63]
	v_mfma_f32_16x16x32_bf16 v[56:59], v[140:143], v[192:195], v[56:59]
	v_mfma_f32_16x16x32_bf16 v[44:47], v[132:135], v[200:203], v[44:47]
	v_mfma_f32_16x16x32_bf16 v[40:43], v[140:143], v[200:203], v[40:43]
	v_mfma_f32_16x16x32_bf16 v[28:31], v[132:135], v[208:211], v[28:31]
	v_mfma_f32_16x16x32_bf16 v[24:27], v[140:143], v[208:211], v[24:27]
	v_mfma_f32_16x16x32_bf16 v[12:15], v[132:135], v[230:233], v[12:15]
	v_mfma_f32_16x16x32_bf16 v[8:11], v[140:143], v[230:233], v[8:11]
	s_setprio 0
	s_setprio 1
	v_mfma_f32_16x16x32_bf16 v[48:51], v[154:157], v[176:179], v[48:51]
	v_mfma_f32_16x16x32_bf16 v[52:55], v[168:171], v[176:179], v[52:55]
	v_mfma_f32_16x16x32_bf16 v[32:35], v[154:157], v[196:199], v[32:35]
	v_mfma_f32_16x16x32_bf16 v[36:39], v[168:171], v[196:199], v[36:39]
	v_mfma_f32_16x16x32_bf16 v[16:19], v[154:157], v[204:207], v[16:19]
	v_mfma_f32_16x16x32_bf16 v[20:23], v[168:171], v[204:207], v[20:23]
	v_mfma_f32_16x16x32_bf16 v[0:3], v[154:157], v[212:215], v[0:3]
	v_mfma_f32_16x16x32_bf16 v[4:7], v[168:171], v[212:215], v[4:7]
	v_mfma_f32_16x16x32_bf16 v[48:51], v[164:167], v[192:195], v[48:51]
	v_mfma_f32_16x16x32_bf16 v[52:55], v[172:175], v[192:195], v[52:55]
	v_mfma_f32_16x16x32_bf16 v[32:35], v[164:167], v[200:203], v[32:35]
	v_mfma_f32_16x16x32_bf16 v[36:39], v[172:175], v[200:203], v[36:39]
	v_mfma_f32_16x16x32_bf16 v[16:19], v[164:167], v[208:211], v[16:19]
	v_mfma_f32_16x16x32_bf16 v[20:23], v[172:175], v[208:211], v[20:23]
	v_mfma_f32_16x16x32_bf16 v[0:3], v[164:167], v[230:233], v[0:3]
	v_mfma_f32_16x16x32_bf16 v[4:7], v[172:175], v[230:233], v[4:7]
	s_setprio 0
	s_barrier
	s_add_i32 s48, s48, 2
	s_add_u32 s22, s22, 0x100
	s_addc_u32 s23, s23, 0
	s_add_u32 s46, s46, 0x100
	s_addc_u32 s47, s47, 0
	s_cmp_gt_u32 s48, 13
	s_cbranch_scc0 .LBB0_744
	s_and_b64 vcc, exec, s[6:7]
	s_cbranch_vccz .LBB0_747
	s_barrier
